# plus grid barrier: non-last workgroups of an XCD poll the top-level generation word directly, per-XCD release word dropped (one round trip less per barrier)
# baseline (speedup 1.0000x reference)
.LBB0_1238:
	s_or_b64 exec, exec, s[24:25]
	v_cvt_f32_u32_e32 v5, v2
	s_waitcnt vmcnt(0)
	v_readfirstlane_b32 s24, v4
	v_sub_u32_e32 v4, 0, v2
	v_rcp_iflag_f32_e32 v5, v5
	v_add_u32_e32 v6, s24, v1
	v_mul_f32_e32 v5, 0x4f7ffffe, v5
	v_cvt_u32_f32_e32 v5, v5
	v_mul_lo_u32 v1, v4, v5
	v_mul_hi_u32 v1, v5, v1
	v_add_u32_e32 v1, v5, v1
	v_mul_hi_u32 v1, v6, v1
	v_mul_lo_u32 v4, v1, v2
	v_sub_u32_e32 v4, v6, v4
	v_add_u32_e32 v5, 1, v1
	v_cmp_ge_u32_e32 vcc, v4, v2
	s_nop 1
	v_cndmask_b32_e32 v1, v1, v5, vcc
	v_sub_u32_e32 v5, v4, v2
	v_cndmask_b32_e32 v4, v4, v5, vcc
	v_add_u32_e32 v5, 1, v1
	v_cmp_ge_u32_e32 vcc, v4, v2
	v_add_u32_e32 v4, 1, v6
	s_nop 0
	v_cndmask_b32_e32 v1, v1, v5, vcc
	v_mul_lo_u32 v5, v2, v1
	v_add_u32_e32 v2, v5, v2
	v_cmp_ne_u32_e32 vcc, v4, v2
	s_and_saveexec_b64 s[24:25], vcc
	s_xor_b64 s[24:25], exec, s[24:25]
	s_cbranch_execz .LBB0_1252
	v_readlane_b32 s26, v235, 33
	v_readlane_b32 s27, v235, 34
	s_waitcnt lgkmcnt(0)
	s_nop 3
	global_load_dword v0, v3, s[26:27] sc1
	s_waitcnt vmcnt(0)
	v_cmp_eq_u32_e32 vcc, v0, v1
	s_and_saveexec_b64 s[26:27], vcc
	s_cbranch_execz .LBB0_1251
	s_mov_b32 s44, 1
	s_mov_b64 s[28:29], 0
	s_branch .LBB0_1242

.LBB0_1244:
	v_readlane_b32 s34, v235, 33
	v_readlane_b32 s35, v235, 34
	s_add_i32 s44, s44, 1
	s_mov_b64 s[36:37], -1
	s_nop 2
	global_load_dword v0, v3, s[34:35] sc1
	s_waitcnt vmcnt(0)
	v_cmp_ne_u32_e32 vcc, v0, v1
	s_orn2_b64 s[34:35], vcc, exec
	s_branch .LBB0_1241

.LBB0_1288:
	s_getpc_b64 s[98:99]
